# rms-norm style wave all-reduces (NORM x8, LATNORM, FINAL, HG readout): six serial ds_bpermute round trips -> permlane32/16 swaps + DPP moves (row_ror:8, row_half_mirror, quad_perm)
# speedup vs baseline: 1.0027x; 1.0027x over previous
.LBB0_224:
	s_or_b64 exec, exec, s[8:9]
	s_waitcnt vmcnt(2)
	v_mov_b32_e32 v18, v10
	v_mov_b32_e32 v19, v14
	v_pk_mul_f32 v[18:19], v[18:19], v[18:19]
	v_mov_b32_e32 v20, v11
	v_mov_b32_e32 v21, v15
	v_pk_fma_f32 v[18:19], v[20:21], v[20:21], v[18:19]
	v_mov_b32_e32 v20, v12
	v_mov_b32_e32 v21, v16
	v_pk_fma_f32 v[18:19], v[20:21], v[20:21], v[18:19]
	v_mov_b32_e32 v20, v13
	v_mov_b32_e32 v21, v17
	v_pk_fma_f32 v[18:19], v[20:21], v[20:21], v[18:19]
	s_waitcnt vmcnt(0)
	v_mov_b32_e32 v20, v2
	v_mov_b32_e32 v21, v6
	v_pk_mul_f32 v[20:21], v[20:21], v[20:21]
	v_mov_b32_e32 v40, v3
	v_mov_b32_e32 v41, v7
	v_pk_fma_f32 v[20:21], v[40:41], v[40:41], v[20:21]
	v_mov_b32_e32 v40, v4
	v_mov_b32_e32 v41, v8
	v_pk_fma_f32 v[20:21], v[40:41], v[40:41], v[20:21]
	v_mov_b32_e32 v40, v5
	v_mov_b32_e32 v41, v9
	v_pk_fma_f32 v[20:21], v[40:41], v[40:41], v[20:21]
	global_load_dwordx4 v[40:43], v[24:25], off
	v_add_f32_e32 v0, v18, v19
	v_add_f32_e32 v0, v21, v0
	v_add_f32_e32 v0, v20, v0
	v_mov_b32_e32 v18, v0
	s_nop 1
	v_permlane32_swap_b32_e32 v18, v0
	s_mov_b32 s2, 0x800000
	v_add_f32_e32 v0, v0, v18
	v_mov_b32_e32 v18, v0
	s_nop 1
	v_permlane16_swap_b32_e32 v18, v0
	v_add_f32_e32 v0, v0, v18
	s_nop 1
	v_mov_b32_dpp v18, v0 row_ror:8 row_mask:0xf bank_mask:0xf
	v_add_f32_e32 v0, v0, v18
	s_nop 1
	v_mov_b32_dpp v18, v0 row_half_mirror row_mask:0xf bank_mask:0xf
	v_add_f32_e32 v0, v0, v18
	s_nop 1
	v_mov_b32_dpp v18, v0 quad_perm:[2,3,0,1] row_mask:0xf bank_mask:0xf
	v_add_f32_e32 v0, v0, v18
	s_nop 1
	v_mov_b32_dpp v18, v0 quad_perm:[1,0,3,2] row_mask:0xf bank_mask:0xf
	v_add_f32_e32 v0, v0, v18
	v_fmamk_f32 v0, v0, 0x3a800000, v162
	v_cmp_gt_f32_e32 vcc, s2, v0
	v_mul_f32_e32 v18, 0x4b800000, v0
	v_readlane_b32 s2, v252, 59
	v_cndmask_b32_e32 v0, v0, v18, vcc
	v_rsq_f32_e32 v0, v0
	s_nop 0
	v_mul_f32_e32 v18, 0x45800000, v0
	v_cndmask_b32_e32 v0, v0, v18, vcc
	v_lshlrev_b64 v[18:19], 12, v[22:23]
	v_pk_mul_f32 v[14:15], v[14:15], v[0:1] op_sel_hi:[1,0]
	v_pk_mul_f32 v[16:17], v[16:17], v[0:1] op_sel_hi:[1,0]
	v_lshl_add_u64 v[18:19], v[28:29], 0, v[18:19]
	v_pk_mul_f32 v[12:13], v[12:13], v[0:1] op_sel_hi:[1,0]
	v_pk_mul_f32 v[10:11], v[10:11], v[0:1] op_sel_hi:[1,0]
	v_pk_mul_f32 v[8:9], v[8:9], v[0:1] op_sel_hi:[1,0]
	v_pk_mul_f32 v[6:7], v[6:7], v[0:1] op_sel_hi:[1,0]
	v_add_u32_e32 v22, s2, v22
	v_pk_mul_f32 v[4:5], v[4:5], v[0:1] op_sel_hi:[1,0]
	v_pk_mul_f32 v[2:3], v[2:3], v[0:1] op_sel_hi:[1,0]
	v_cmp_lt_i32_e32 vcc, s0, v22
	s_or_b64 s[6:7], vcc, s[6:7]
	s_waitcnt vmcnt(0)
	v_pk_mul_f32 v[16:17], v[42:43], v[16:17]
	v_pk_mul_f32 v[14:15], v[40:41], v[14:15]
	global_store_dwordx4 v[18:19], v[14:17], off nt
	global_load_dwordx4 v[14:17], v[24:25], off offset:1024
	s_waitcnt vmcnt(0)
	v_pk_mul_f32 v[10:11], v[14:15], v[10:11]
	v_pk_mul_f32 v[12:13], v[16:17], v[12:13]
	global_store_dwordx4 v[18:19], v[10:13], off offset:1024 nt
	global_load_dwordx4 v[10:13], v[24:25], off offset:2048
	s_waitcnt vmcnt(0)
	v_pk_mul_f32 v[6:7], v[10:11], v[6:7]
	v_pk_mul_f32 v[8:9], v[12:13], v[8:9]
	global_store_dwordx4 v[18:19], v[6:9], off offset:2048 nt
	global_load_dwordx4 v[6:9], v[24:25], off offset:3072
	s_waitcnt vmcnt(0)
	v_pk_mul_f32 v[2:3], v[2:3], v[6:7]
	v_pk_mul_f32 v[4:5], v[4:5], v[8:9]
	global_store_dwordx4 v[18:19], v[2:5], off offset:3072 nt
	s_andn2_b64 exec, exec, s[6:7]
	s_cbranch_execz .LBB0_228

.LBB0_428:
	v_ashrrev_i32_e32 v3, 31, v2
	s_waitcnt vmcnt(0)
	v_lshlrev_b64 v[20:21], 11, v[2:3]
	v_lshl_or_b32 v20, v4, 1, v20
	v_lshl_add_u64 v[24:25], s[10:11], 0, v[20:21]
	v_lshl_add_u64 v[28:29], s[38:39], 0, v[20:21]
	s_waitcnt lgkmcnt(0)
	global_load_dwordx4 v[12:15], v[24:25], off offset:16
	global_load_dwordx4 v[16:19], v[28:29], off offset:16
	v_lshl_add_u64 v[32:33], s[8:9], 0, v[20:21]
	global_load_dwordx4 v[20:23], v[32:33], off offset:16
	s_nop 0
	global_load_dwordx4 v[24:27], v[24:25], off
	s_nop 0
	global_load_dwordx4 v[28:31], v[28:29], off
	s_nop 0
	global_load_dwordx4 v[32:35], v[32:33], off
	s_nop 0
	global_load_dwordx4 v[36:39], v[6:7], off offset:48
	global_load_dwordx4 v[40:43], v[6:7], off offset:32
	global_load_dwordx4 v[44:47], v[6:7], off offset:16
	global_load_dwordx4 v[48:51], v[6:7], off
	s_movk_i32 s2, 0x43ff
	s_waitcnt vmcnt(7)
	v_and_b32_e32 v57, 0xffff0000, v20
	s_waitcnt vmcnt(6)
	v_and_b32_e32 v67, 0xffff0000, v25
	s_waitcnt vmcnt(5)
	v_and_b32_e32 v65, 0xffff0000, v28
	v_lshlrev_b32_e32 v64, 16, v28
	v_and_b32_e32 v53, 0xffff0000, v12
	v_lshlrev_b32_e32 v52, 16, v12
	v_and_b32_e32 v55, 0xffff0000, v16
	v_lshlrev_b32_e32 v54, 16, v16
	v_and_b32_e32 v59, 0xffff0000, v13
	v_lshlrev_b32_e32 v58, 16, v13
	v_and_b32_e32 v13, 0xffff0000, v17
	v_lshlrev_b32_e32 v12, 16, v17
	v_and_b32_e32 v17, 0xffff0000, v14
	v_lshlrev_b32_e32 v16, 16, v14
	v_and_b32_e32 v61, 0xffff0000, v18
	v_lshlrev_b32_e32 v60, 16, v18
	v_and_b32_e32 v63, 0xffff0000, v15
	v_lshlrev_b32_e32 v62, 16, v15
	v_and_b32_e32 v15, 0xffff0000, v19
	v_lshlrev_b32_e32 v14, 16, v19
	v_and_b32_e32 v19, 0xffff0000, v24
	v_lshlrev_b32_e32 v18, 16, v24
	v_lshlrev_b32_e32 v66, 16, v25
	v_and_b32_e32 v25, 0xffff0000, v29
	v_lshlrev_b32_e32 v24, 16, v29
	v_pk_add_f32 v[18:19], v[18:19], v[64:65]
	v_pk_add_f32 v[14:15], v[62:63], v[14:15]
	v_pk_add_f32 v[24:25], v[66:67], v[24:25]
	v_pk_mul_f32 v[62:63], v[18:19], v[18:19]
	v_and_b32_e32 v29, 0xffff0000, v26
	v_lshlrev_b32_e32 v28, 16, v26
	v_and_b32_e32 v69, 0xffff0000, v30
	v_lshlrev_b32_e32 v68, 16, v30
	v_pk_mul_f32 v[64:65], v[24:25], v[24:25]
	v_add_f32_e32 v0, v62, v63
	v_pk_add_f32 v[28:29], v[28:29], v[68:69]
	v_add_f32_e32 v0, v64, v0
	v_and_b32_e32 v71, 0xffff0000, v27
	v_lshlrev_b32_e32 v70, 16, v27
	v_and_b32_e32 v27, 0xffff0000, v31
	v_lshlrev_b32_e32 v26, 16, v31
	v_pk_mul_f32 v[66:67], v[28:29], v[28:29]
	v_add_f32_e32 v0, v65, v0
	v_pk_add_f32 v[26:27], v[70:71], v[26:27]
	v_add_f32_e32 v0, v66, v0
	v_pk_mul_f32 v[68:69], v[26:27], v[26:27]
	v_add_f32_e32 v0, v67, v0
	v_pk_add_f32 v[30:31], v[52:53], v[54:55]
	v_add_f32_e32 v0, v68, v0
	v_pk_mul_f32 v[52:53], v[30:31], v[30:31]
	v_add_f32_e32 v0, v69, v0
	v_pk_add_f32 v[12:13], v[58:59], v[12:13]
	v_add_f32_e32 v0, v52, v0
	v_pk_mul_f32 v[54:55], v[12:13], v[12:13]
	v_add_f32_e32 v0, v53, v0
	v_pk_add_f32 v[16:17], v[16:17], v[60:61]
	v_add_f32_e32 v0, v54, v0
	v_pk_mul_f32 v[58:59], v[16:17], v[16:17]
	v_add_f32_e32 v0, v55, v0
	v_add_f32_e32 v0, v58, v0
	v_pk_mul_f32 v[60:61], v[14:15], v[14:15]
	v_add_f32_e32 v0, v59, v0
	v_add_f32_e32 v0, v60, v0
	v_add_f32_e32 v0, v61, v0
	s_nop 1
	v_mov_b32_dpp v54, v0 quad_perm:[1,0,3,2] row_mask:0xf bank_mask:0xf
	v_lshlrev_b32_e32 v56, 16, v20
	v_and_b32_e32 v53, 0xffff0000, v21
	v_lshlrev_b32_e32 v52, 16, v21
	v_and_b32_e32 v21, 0xffff0000, v22
	v_add_f32_e32 v0, v0, v54
	s_nop 1
	v_mov_b32_dpp v58, v0 quad_perm:[2,3,0,1] row_mask:0xf bank_mask:0xf
	v_lshlrev_b32_e32 v20, 16, v22
	s_waitcnt vmcnt(4)
	v_and_b32_e32 v55, 0xffff0000, v32
	v_lshlrev_b32_e32 v54, 16, v32
	v_and_b32_e32 v59, 0xffff0000, v33
	v_add_f32_e32 v0, v0, v58
	s_nop 1
	v_mov_b32_dpp v22, v0 row_half_mirror row_mask:0xf bank_mask:0xf
	v_lshlrev_b32_e32 v58, 16, v33
	v_and_b32_e32 v33, 0xffff0000, v34
	v_lshlrev_b32_e32 v32, 16, v34
	v_and_b32_e32 v61, 0xffff0000, v23
	v_add_f32_e32 v0, v0, v22
	v_fmamk_f32 v0, v0, 0x3c000000, v162
	v_mul_f32_e32 v22, 0x4b800000, v0
	v_cmp_gt_f32_e32 vcc, s15, v0
	v_lshlrev_b32_e32 v60, 16, v23
	v_and_b32_e32 v23, 0xffff0000, v35
	v_cndmask_b32_e32 v0, v0, v22, vcc
	v_rsq_f32_e32 v0, v0
	v_lshlrev_b32_e32 v22, 16, v35
	v_mul_f32_e32 v34, 0x45800000, v0
	v_cndmask_b32_e32 v0, v0, v34, vcc
	v_pk_mul_f32 v[18:19], v[18:19], v[0:1] op_sel_hi:[1,0]
	v_pk_mul_f32 v[24:25], v[24:25], v[0:1] op_sel_hi:[1,0]
	v_pk_mul_f32 v[12:13], v[12:13], v[0:1] op_sel_hi:[1,0]
	v_pk_mul_f32 v[28:29], v[28:29], v[0:1] op_sel_hi:[1,0]
	v_pk_mul_f32 v[16:17], v[16:17], v[0:1] op_sel_hi:[1,0]
	v_pk_mul_f32 v[26:27], v[26:27], v[0:1] op_sel_hi:[1,0]
	v_pk_mul_f32 v[14:15], v[14:15], v[0:1] op_sel_hi:[1,0]
	s_waitcnt vmcnt(0)
	v_pk_mul_f32 v[18:19], v[48:49], v[18:19]
	v_pk_mul_f32 v[24:25], v[50:51], v[24:25]
	v_pk_mul_f32 v[12:13], v[42:43], v[12:13]
	v_pk_mul_f32 v[28:29], v[44:45], v[28:29]
	v_pk_mul_f32 v[16:17], v[36:37], v[16:17]
	v_pk_mul_f32 v[26:27], v[46:47], v[26:27]
	v_pk_mul_f32 v[14:15], v[38:39], v[14:15]
	v_pk_mul_f32 v[18:19], v[18:19], v[54:55]
	v_pk_mul_f32 v[24:25], v[24:25], v[58:59]
	v_pk_mul_f32 v[34:35], v[12:13], v[52:53]
	v_pk_mul_f32 v[12:13], v[28:29], v[32:33]
	v_pk_mul_f32 v[16:17], v[16:17], v[20:21]
	v_pk_mul_f32 v[20:21], v[26:27], v[22:23]
	v_pk_mul_f32 v[30:31], v[30:31], v[0:1] op_sel_hi:[1,0]
	v_pk_mul_f32 v[22:23], v[14:15], v[60:61]
	v_pk_mul_f32 v[30:31], v[40:41], v[30:31]
	v_cvt_pk_bf16_f32 v15, v20, v21
	v_cvt_pk_bf16_f32 v14, v12, v13
	v_cvt_pk_bf16_f32 v13, v24, v25
	v_cvt_pk_bf16_f32 v12, v18, v19
	v_pk_mul_f32 v[30:31], v[30:31], v[56:57]
	v_cvt_pk_bf16_f32 v19, v22, v23
	v_cvt_pk_bf16_f32 v18, v16, v17
	v_cvt_pk_bf16_f32 v17, v34, v35
	v_lshl_add_u64 v[20:21], s[56:57], 0, v[2:3]
	v_add_u32_e32 v2, s14, v2
	v_lshlrev_b64 v[20:21], 11, v[20:21]
	v_cmp_lt_i32_e32 vcc, s2, v2
	v_cvt_pk_bf16_f32 v16, v30, v31
	v_lshl_add_u64 v[20:21], v[8:9], 0, v[20:21]
	s_or_b64 s[6:7], vcc, s[6:7]
	global_store_dwordx4 v[20:21], v[12:15], off
	global_store_dwordx4 v[20:21], v[16:19], off offset:16
	s_andn2_b64 exec, exec, s[6:7]
	s_cbranch_execnz .LBB0_428

.LBB0_594:
	s_movk_i32 s8, 0xa80
	s_waitcnt lgkmcnt(0)
	v_mad_i64_i32 v[12:13], s[8:9], v2, s8, v[10:11]
	global_load_dword v31, v[12:13], off offset:256
	global_load_dword v32, v[12:13], off offset:512
	global_load_dword v33, v[12:13], off offset:768
	global_load_dword v34, v[12:13], off offset:1024
	global_load_dword v35, v[12:13], off offset:1280
	global_load_dword v36, v[12:13], off offset:1536
	global_load_dword v37, v[12:13], off offset:1792
	global_load_dword v38, v[12:13], off offset:2048
	global_load_dword v39, v[12:13], off offset:2304
	global_load_dword v30, v[12:13], off
	s_movk_i32 s8, 0x300
	s_mov_b32 s10, 0x800000
	v_ashrrev_i32_e32 v3, 31, v2
	s_waitcnt vmcnt(9)
	v_mul_f32_e32 v40, v31, v31
	s_waitcnt vmcnt(7)
	v_pk_mul_f32 v[42:43], v[32:33], v[32:33]
	s_waitcnt vmcnt(5)
	v_pk_mul_f32 v[44:45], v[34:35], v[34:35]
	s_nop 0
	v_mov_b32_e32 v51, v44
	s_waitcnt vmcnt(3)
	v_pk_mul_f32 v[46:47], v[36:37], v[36:37]
	s_waitcnt vmcnt(1)
	v_pk_mul_f32 v[48:49], v[38:39], v[38:39]
	s_waitcnt vmcnt(0)
	v_pk_fma_f32 v[40:41], v[30:31], v[30:31], v[40:41] op_sel_hi:[1,1,0]
	v_mov_b32_e32 v42, v47
	v_pk_fma_f32 v[40:41], v[32:33], v[32:33], v[40:41]
	v_mov_b32_e32 v50, v48
	v_mov_b32_e32 v47, v40
	v_pk_add_f32 v[40:41], v[46:47], v[42:43]
	v_mov_b32_e32 v44, v49
	v_pk_add_f32 v[40:41], v[40:41], v[50:51]
	s_nop 0
	v_pk_add_f32 v[40:41], v[40:41], v[44:45]
	v_mov_b32_e32 v43, v41
	v_mov_b32_e32 v42, v40
	s_nop 0
	v_permlane32_swap_b32_e32 v43, v41
	v_permlane32_swap_b32_e32 v42, v40
	v_mad_i64_i32 v[44:45], s[8:9], v2, s8, v[4:5]
	s_mov_b32 s8, 0x3b800000
	s_mov_b32 s9, 0x3b2aaaab
	v_pk_add_f32 v[40:41], v[40:41], v[42:43]
	v_mov_b32_e32 v43, v41
	v_mov_b32_e32 v42, v40
	s_nop 0
	v_permlane16_swap_b32_e32 v43, v41
	v_permlane16_swap_b32_e32 v42, v40
	v_pk_add_f32 v[40:41], v[40:41], v[42:43]
	s_nop 1
	v_mov_b32_dpp v43, v41 row_ror:8 row_mask:0xf bank_mask:0xf
	v_mov_b32_dpp v42, v40 row_ror:8 row_mask:0xf bank_mask:0xf
	v_pk_add_f32 v[40:41], v[40:41], v[42:43]
	s_nop 1
	v_mov_b32_dpp v43, v41 row_half_mirror row_mask:0xf bank_mask:0xf
	v_mov_b32_dpp v42, v40 row_half_mirror row_mask:0xf bank_mask:0xf
	v_pk_add_f32 v[40:41], v[40:41], v[42:43]
	s_nop 1
	v_mov_b32_dpp v43, v41 quad_perm:[2,3,0,1] row_mask:0xf bank_mask:0xf
	v_mov_b32_dpp v42, v40 quad_perm:[2,3,0,1] row_mask:0xf bank_mask:0xf
	v_pk_add_f32 v[40:41], v[40:41], v[42:43]
	s_nop 1
	v_mov_b32_dpp v43, v41 quad_perm:[1,0,3,2] row_mask:0xf bank_mask:0xf
	v_mov_b32_dpp v42, v40 quad_perm:[1,0,3,2] row_mask:0xf bank_mask:0xf
	v_pk_add_f32 v[40:41], v[40:41], v[42:43]
	s_nop 0
	v_pk_fma_f32 v[40:41], v[40:41], s[8:9], v[162:163] op_sel_hi:[1,1,0]
	s_nop 0
	v_mul_f32_e32 v42, 0x4b800000, v41
	v_cmp_gt_f32_e64 s[8:9], s10, v41
	v_mul_f32_e32 v43, 0x4b800000, v40
	v_cmp_gt_f32_e64 s[10:11], s10, v40
	v_cndmask_b32_e64 v41, v41, v42, s[8:9]
	v_rsq_f32_e32 v42, v41
	v_cndmask_b32_e64 v40, v40, v43, s[10:11]
	v_rsq_f32_e32 v43, v40
	v_lshlrev_b64 v[40:41], 9, v[2:3]
	v_mul_f32_e32 v46, 0x45800000, v42
	v_cndmask_b32_e64 v42, v42, v46, s[8:9]
	v_mul_f32_e32 v47, 0x45800000, v43
	v_cndmask_b32_e64 v43, v43, v47, s[10:11]
	v_mul_f32_e32 v30, v30, v42
	v_mul_f32_e32 v31, v31, v42
	v_mul_f32_e32 v32, v32, v42
	v_mul_f32_e32 v33, v33, v42
	v_mul_f32_e32 v34, v34, v42
	v_mul_f32_e32 v35, v35, v42
	v_mul_f32_e32 v36, v36, v43
	v_mul_f32_e32 v37, v37, v43
	v_mul_f32_e32 v38, v38, v43
	v_mul_f32_e32 v39, v39, v43
	v_mul_f32_e32 v30, v14, v30
	v_mul_f32_e32 v31, v15, v31
	v_mul_f32_e32 v32, v16, v32
	v_mul_f32_e32 v33, v17, v33
	v_mul_f32_e32 v34, v18, v34
	v_mul_f32_e32 v35, v19, v35
	v_mul_f32_e32 v36, v20, v36
	v_mul_f32_e32 v37, v21, v37
	v_mul_f32_e32 v38, v22, v38
	v_mul_f32_e32 v39, v23, v39
	v_bfe_u32 v42, v30, 16, 1
	v_bfe_u32 v43, v31, 16, 1
	v_bfe_u32 v46, v32, 16, 1
	v_bfe_u32 v47, v33, 16, 1
	v_bfe_u32 v48, v34, 16, 1
	v_bfe_u32 v49, v35, 16, 1
	v_bfe_u32 v50, v36, 16, 1
	v_bfe_u32 v51, v37, 16, 1
	v_bfe_u32 v52, v38, 16, 1
	v_bfe_u32 v53, v39, 16, 1
	v_add3_u32 v30, v30, v42, s0
	v_lshl_add_u64 v[40:41], v[6:7], 0, v[40:41]
	v_add3_u32 v31, v31, v43, s0
	v_add3_u32 v32, v32, v46, s0
	v_add3_u32 v33, v33, v47, s0
	v_add3_u32 v34, v34, v48, s0
	v_add3_u32 v35, v35, v49, s0
	v_add3_u32 v36, v36, v50, s0
	v_add3_u32 v37, v37, v51, s0
	v_add3_u32 v38, v38, v52, s0
	v_add3_u32 v39, v39, v53, s0
	global_store_short_d16_hi v[44:45], v30, off
	global_store_short_d16_hi v[44:45], v31, off offset:128
	global_store_short_d16_hi v[44:45], v32, off offset:256
	global_store_short_d16_hi v[44:45], v33, off offset:384
	global_store_short_d16_hi v[44:45], v34, off offset:512
	global_store_short_d16_hi v[44:45], v35, off offset:640
	global_store_short_d16_hi v[40:41], v36, off
	global_store_short_d16_hi v[40:41], v37, off offset:128
	global_store_short_d16_hi v[40:41], v38, off offset:256
	global_store_short_d16_hi v[40:41], v39, off offset:384
	v_mov_b32_e32 v30, 0
	s_and_saveexec_b64 s[8:9], vcc
	s_cbranch_execz .LBB0_596
	global_load_dword v30, v[12:13], off offset:2560

.LBB0_1287:
	s_or_b64 exec, exec, s[4:5]
	s_waitcnt vmcnt(14)
	v_mov_b32_e32 v66, v14
	v_mov_b32_e32 v67, v34
	v_pk_mul_f32 v[66:67], v[66:67], v[66:67]
	v_mov_b32_e32 v68, v15
	v_mov_b32_e32 v69, v35
	v_pk_fma_f32 v[66:67], v[68:69], v[68:69], v[66:67]
	v_mov_b32_e32 v68, v16
	v_mov_b32_e32 v69, v36
	v_pk_fma_f32 v[66:67], v[68:69], v[68:69], v[66:67]
	v_mov_b32_e32 v68, v17
	v_mov_b32_e32 v69, v37
	v_pk_fma_f32 v[66:67], v[68:69], v[68:69], v[66:67]
	s_waitcnt vmcnt(12)
	v_mov_b32_e32 v68, v2
	v_mov_b32_e32 v69, v6
	v_pk_mul_f32 v[68:69], v[68:69], v[68:69]
	v_mov_b32_e32 v104, v3
	v_mov_b32_e32 v105, v7
	v_pk_fma_f32 v[68:69], v[104:105], v[104:105], v[68:69]
	v_mov_b32_e32 v104, v4
	v_mov_b32_e32 v105, v8
	v_pk_fma_f32 v[68:69], v[104:105], v[104:105], v[68:69]
	v_mov_b32_e32 v104, v5
	v_mov_b32_e32 v105, v9
	v_pk_fma_f32 v[68:69], v[104:105], v[104:105], v[68:69]
	s_waitcnt vmcnt(10)
	v_mov_b32_e32 v104, v26
	v_mov_b32_e32 v105, v46
	v_pk_mul_f32 v[104:105], v[104:105], v[104:105]
	v_mov_b32_e32 v106, v27
	v_mov_b32_e32 v107, v47
	v_pk_fma_f32 v[104:105], v[106:107], v[106:107], v[104:105]
	v_mov_b32_e32 v106, v28
	v_mov_b32_e32 v107, v48
	v_pk_fma_f32 v[104:105], v[106:107], v[106:107], v[104:105]
	v_mov_b32_e32 v106, v29
	v_mov_b32_e32 v107, v49
	v_pk_fma_f32 v[104:105], v[106:107], v[106:107], v[104:105]
	s_waitcnt vmcnt(8)
	v_mov_b32_e32 v106, v10
	v_mov_b32_e32 v107, v18
	v_pk_mul_f32 v[106:107], v[106:107], v[106:107]
	v_mov_b32_e32 v108, v11
	v_mov_b32_e32 v109, v19
	v_pk_fma_f32 v[106:107], v[108:109], v[108:109], v[106:107]
	v_mov_b32_e32 v108, v12
	v_mov_b32_e32 v109, v20
	v_pk_fma_f32 v[106:107], v[108:109], v[108:109], v[106:107]
	v_mov_b32_e32 v108, v13
	v_mov_b32_e32 v109, v21
	v_pk_fma_f32 v[106:107], v[108:109], v[108:109], v[106:107]
	v_mov_b32_e32 v108, v104
	v_mov_b32_e32 v109, v66
	v_mov_b32_e32 v66, v105
	v_pk_add_f32 v[66:67], v[108:109], v[66:67]
	v_mov_b32_e32 v104, v107
	v_mov_b32_e32 v105, v69
	v_pk_add_f32 v[66:67], v[104:105], v[66:67]
	v_mov_b32_e32 v107, v68
	v_pk_add_f32 v[66:67], v[106:107], v[66:67]
	v_mov_b32_e32 v69, v67
	v_mov_b32_e32 v68, v66
	s_nop 0
	v_permlane32_swap_b32_e32 v69, v67
	v_permlane32_swap_b32_e32 v68, v66
	s_mov_b32 s4, 0x358637bd
	s_mov_b32 s24, 0x3a800000
	s_mov_b32 s14, 0x800000
	s_waitcnt vmcnt(6)
	v_mov_b32_e32 v108, v39
	v_pk_add_f32 v[66:67], v[66:67], v[68:69]
	v_mov_b32_e32 v69, v67
	v_mov_b32_e32 v68, v66
	s_nop 0
	v_permlane16_swap_b32_e32 v69, v67
	v_permlane16_swap_b32_e32 v68, v66
	v_mov_b32_e32 v109, v55
	s_waitcnt vmcnt(4)
	v_mov_b32_e32 v110, v23
	v_mov_b32_e32 v111, v31
	s_waitcnt vmcnt(2)
	v_mov_b32_e32 v112, v59
	v_pk_add_f32 v[66:67], v[66:67], v[68:69]
	s_nop 1
	v_mov_b32_dpp v69, v67 row_ror:8 row_mask:0xf bank_mask:0xf
	v_mov_b32_dpp v68, v66 row_ror:8 row_mask:0xf bank_mask:0xf
	v_mov_b32_e32 v113, v63
	s_waitcnt vmcnt(1)
	v_mov_b32_e32 v114, v50
	s_waitcnt vmcnt(0)
	v_mov_b32_e32 v115, v43
	v_pk_mul_f32 v[114:115], v[114:115], v[114:115]
	v_pk_add_f32 v[66:67], v[66:67], v[68:69]
	s_nop 1
	v_mov_b32_dpp v69, v67 row_half_mirror row_mask:0xf bank_mask:0xf
	v_mov_b32_dpp v68, v66 row_half_mirror row_mask:0xf bank_mask:0xf
	v_mov_b32_e32 v95, v1
	v_pk_add_f32 v[66:67], v[66:67], v[68:69]
	s_nop 1
	v_mov_b32_dpp v69, v67 quad_perm:[2,3,0,1] row_mask:0xf bank_mask:0xf
	v_mov_b32_dpp v68, v66 quad_perm:[2,3,0,1] row_mask:0xf bank_mask:0xf
	v_pk_add_f32 v[66:67], v[66:67], v[68:69]
	s_nop 1
	v_mov_b32_dpp v69, v67 quad_perm:[1,0,3,2] row_mask:0xf bank_mask:0xf
	v_mov_b32_dpp v68, v66 quad_perm:[1,0,3,2] row_mask:0xf bank_mask:0xf
	v_pk_add_f32 v[66:67], v[66:67], v[68:69]
	v_mov_b64_e32 v[68:69], s[4:5]
	v_pk_fma_f32 v[66:67], v[66:67], s[24:25], v[68:69] op_sel_hi:[1,0,0]
	s_nop 0
	v_mul_f32_e32 v89, 0x4b800000, v67
	v_cmp_gt_f32_e64 s[4:5], s14, v67
	v_cmp_gt_f32_e32 vcc, s14, v66
	s_nop 0
	v_cndmask_b32_e64 v67, v67, v89, s[4:5]
	v_rsq_f32_e32 v67, v67
	s_nop 0
	v_mul_f32_e32 v89, 0x45800000, v67
	v_cndmask_b32_e64 v106, v67, v89, s[4:5]
	v_mul_f32_e32 v67, 0x4b800000, v66
	v_cndmask_b32_e32 v66, v66, v67, vcc
	v_rsq_f32_e32 v66, v66
	v_pk_mul_f32 v[34:35], v[34:35], v[106:107] op_sel_hi:[1,0]
	v_pk_mul_f32 v[36:37], v[36:37], v[106:107] op_sel_hi:[1,0]
	v_pk_mul_f32 v[14:15], v[14:15], v[106:107] op_sel_hi:[1,0]
	v_mul_f32_e32 v67, 0x45800000, v66
	v_cndmask_b32_e32 v104, v66, v67, vcc
	v_mov_b32_e32 v66, v38
	v_mov_b32_e32 v67, v54
	v_pk_mul_f32 v[66:67], v[66:67], v[66:67]
	v_pk_mul_f32 v[16:17], v[16:17], v[106:107] op_sel_hi:[1,0]
	v_pk_fma_f32 v[66:67], v[108:109], v[108:109], v[66:67]
	v_mov_b32_e32 v108, v40
	v_mov_b32_e32 v109, v56
	v_pk_fma_f32 v[66:67], v[108:109], v[108:109], v[66:67]
	v_mov_b32_e32 v108, v41
	v_mov_b32_e32 v109, v57
	v_pk_fma_f32 v[66:67], v[108:109], v[108:109], v[66:67]
	v_mov_b32_e32 v108, v22
	v_mov_b32_e32 v109, v30
	v_pk_mul_f32 v[108:109], v[108:109], v[108:109]
	v_pk_mul_f32 v[6:7], v[6:7], v[106:107] op_sel_hi:[1,0]
	v_pk_fma_f32 v[108:109], v[110:111], v[110:111], v[108:109]
	v_mov_b32_e32 v110, v24
	v_mov_b32_e32 v111, v32
	v_pk_fma_f32 v[108:109], v[110:111], v[110:111], v[108:109]
	v_mov_b32_e32 v110, v25
	v_mov_b32_e32 v111, v33
	v_pk_fma_f32 v[108:109], v[110:111], v[110:111], v[108:109]
	v_mov_b32_e32 v110, v58
	v_mov_b32_e32 v111, v62
	v_pk_mul_f32 v[110:111], v[110:111], v[110:111]
	v_pk_mul_f32 v[8:9], v[8:9], v[106:107] op_sel_hi:[1,0]
	v_pk_fma_f32 v[110:111], v[112:113], v[112:113], v[110:111]
	v_mov_b32_e32 v112, v60
	v_mov_b32_e32 v113, v64
	v_pk_fma_f32 v[110:111], v[112:113], v[112:113], v[110:111]
	v_mov_b32_e32 v112, v61
	v_mov_b32_e32 v113, v65
	v_pk_fma_f32 v[110:111], v[112:113], v[112:113], v[110:111]
	v_pk_mov_b32 v[112:113], v[50:51], v[42:43] op_sel:[1,0]
	v_pk_mul_f32 v[2:3], v[2:3], v[106:107] op_sel_hi:[1,0]
	v_pk_fma_f32 v[112:113], v[112:113], v[112:113], v[114:115]
	v_mov_b32_e32 v114, v52
	v_mov_b32_e32 v115, v44
	v_pk_fma_f32 v[112:113], v[114:115], v[114:115], v[112:113]
	v_mov_b32_e32 v114, v53
	v_mov_b32_e32 v115, v45
	v_pk_fma_f32 v[112:113], v[114:115], v[114:115], v[112:113]
	v_mov_b32_e32 v114, v110
	v_mov_b32_e32 v115, v66
	v_mov_b32_e32 v66, v111
	v_pk_add_f32 v[66:67], v[114:115], v[66:67]
	v_mov_b32_e32 v110, v112
	v_mov_b32_e32 v111, v109
	v_pk_add_f32 v[66:67], v[110:111], v[66:67]
	v_pk_mov_b32 v[108:109], v[112:113], v[108:109] op_sel:[1,0]
	v_pk_mul_f32 v[4:5], v[4:5], v[106:107] op_sel_hi:[1,0]
	v_pk_add_f32 v[66:67], v[66:67], v[108:109]
	v_mov_b32_e32 v109, v67
	v_mov_b32_e32 v108, v66
	s_nop 0
	v_permlane32_swap_b32_e32 v109, v67
	v_permlane32_swap_b32_e32 v108, v66
	v_pk_add_f32 v[66:67], v[66:67], v[108:109]
	v_mov_b32_e32 v109, v67
	v_mov_b32_e32 v108, v66
	s_nop 0
	v_permlane16_swap_b32_e32 v109, v67
	v_permlane16_swap_b32_e32 v108, v66
	v_pk_add_f32 v[66:67], v[66:67], v[108:109]
	s_nop 1
	v_mov_b32_dpp v109, v67 row_ror:8 row_mask:0xf bank_mask:0xf
	v_mov_b32_dpp v108, v66 row_ror:8 row_mask:0xf bank_mask:0xf
	v_pk_add_f32 v[66:67], v[66:67], v[108:109]
	s_nop 1
	v_mov_b32_dpp v109, v67 row_half_mirror row_mask:0xf bank_mask:0xf
	v_mov_b32_dpp v108, v66 row_half_mirror row_mask:0xf bank_mask:0xf
	v_pk_add_f32 v[66:67], v[66:67], v[108:109]
	s_nop 1
	v_mov_b32_dpp v109, v67 quad_perm:[2,3,0,1] row_mask:0xf bank_mask:0xf
	v_mov_b32_dpp v108, v66 quad_perm:[2,3,0,1] row_mask:0xf bank_mask:0xf
	v_pk_add_f32 v[66:67], v[66:67], v[108:109]
	s_nop 1
	v_mov_b32_dpp v109, v67 quad_perm:[1,0,3,2] row_mask:0xf bank_mask:0xf
	v_mov_b32_dpp v108, v66 quad_perm:[1,0,3,2] row_mask:0xf bank_mask:0xf
	v_pk_add_f32 v[66:67], v[66:67], v[108:109]
	s_nop 0
	v_pk_fma_f32 v[66:67], v[66:67], s[24:25], v[68:69] op_sel_hi:[1,0,0]
	s_nop 0
	v_mul_f32_e32 v68, 0x4b800000, v67
	v_cmp_gt_f32_e64 s[4:5], s14, v67
	v_cmp_gt_f32_e32 vcc, s14, v66
	s_nop 0
	v_cndmask_b32_e64 v67, v67, v68, s[4:5]
	v_rsq_f32_e32 v67, v67
	s_nop 0
	v_mul_f32_e32 v68, 0x45800000, v67
	v_cndmask_b32_e64 v110, v67, v68, s[4:5]
	v_mul_f32_e32 v67, 0x4b800000, v66
	v_cndmask_b32_e32 v66, v66, v67, vcc
	v_rsq_f32_e32 v66, v66
	s_mov_b32 s4, 0x8000
	v_mul_f32_e32 v67, 0x45800000, v66
	v_cndmask_b32_e32 v108, v66, v67, vcc
	v_add_u32_e32 v66, v93, v91
	v_mul_i32_i24_e32 v67, 0xffffef00, v66
	v_add3_u32 v67, v67, v88, s4
	v_cmp_lt_i32_e32 vcc, s33, v67
	s_movk_i32 s4, 0x6000
	s_nop 0
	v_cndmask_b32_e32 v66, 8, v66, vcc
	v_add_u32_e32 v68, s30, v66
	v_mov_b64_e32 v[66:67], s[10:11]
	v_mad_i64_i32 v[66:67], s[4:5], v68, s4, v[66:67]
	s_mov_b64 s[4:5], 0x1000
	s_nop 0
	v_lshl_add_u64 v[114:115], v[66:67], 0, s[4:5]
	v_lshl_add_u64 v[68:69], v[114:115], 0, v[0:1]
	v_lshl_add_u64 v[112:113], v[66:67], 0, v[0:1]
	global_load_dwordx4 v[116:119], v[72:73], off
	global_load_dwordx4 v[120:123], v[68:69], off
	s_nop 0
	global_load_dwordx4 v[66:69], v[112:113], off
	v_readlane_b32 s4, v254, 10
	s_waitcnt vmcnt(1)
	v_pk_add_f32 v[120:121], v[120:121], 1.0 op_sel_hi:[1,0]
	s_nop 0
	v_pk_mul_f32 v[116:117], v[116:117], v[120:121]
	v_pk_add_f32 v[120:121], v[122:123], 1.0 op_sel_hi:[1,0]
	s_waitcnt vmcnt(0)
	v_pk_fma_f32 v[34:35], v[34:35], v[116:117], v[66:67]
	v_pk_mul_f32 v[118:119], v[118:119], v[120:121]
	v_pk_fma_f32 v[36:37], v[36:37], v[118:119], v[68:69]
	v_cvt_pk_bf16_f32 v37, v36, v37
	v_cvt_pk_bf16_f32 v36, v34, v35
	v_lshlrev_b64 v[34:35], 11, v[96:97]
	v_lshl_add_u64 v[34:35], v[76:77], 0, v[34:35]
	global_store_dwordx2 v[34:35], v[36:37], off
	v_pk_mul_f32 v[36:37], v[46:47], v[104:105] op_sel_hi:[1,0]
	v_pk_mul_f32 v[46:47], v[48:49], v[104:105] op_sel_hi:[1,0]
	v_pk_fma_f32 v[36:37], v[36:37], v[116:117], v[66:67]
	v_pk_fma_f32 v[46:47], v[46:47], v[118:119], v[68:69]
	v_cvt_pk_bf16_f32 v47, v46, v47
	v_cvt_pk_bf16_f32 v46, v36, v37
	v_lshlrev_b64 v[36:37], 11, v[98:99]
	v_lshl_add_u64 v[36:37], v[76:77], 0, v[36:37]
	global_store_dwordx2 v[36:37], v[46:47], off
	v_pk_mul_f32 v[46:47], v[54:55], v[110:111] op_sel_hi:[1,0]
	v_pk_mul_f32 v[48:49], v[56:57], v[110:111] op_sel_hi:[1,0]
	v_pk_fma_f32 v[46:47], v[46:47], v[116:117], v[66:67]
	v_pk_fma_f32 v[48:49], v[48:49], v[118:119], v[68:69]
	v_cvt_pk_bf16_f32 v49, v48, v49
	v_cvt_pk_bf16_f32 v48, v46, v47
	v_lshlrev_b64 v[46:47], 11, v[100:101]
	v_lshl_add_u64 v[46:47], v[76:77], 0, v[46:47]
	global_store_dwordx2 v[46:47], v[48:49], off
	v_pk_mul_f32 v[48:49], v[62:63], v[108:109] op_sel_hi:[1,0]
	v_pk_mul_f32 v[54:55], v[64:65], v[108:109] op_sel_hi:[1,0]
	v_pk_fma_f32 v[48:49], v[116:117], v[48:49], v[66:67]
	v_pk_fma_f32 v[54:55], v[118:119], v[54:55], v[68:69]
	v_cvt_pk_bf16_f32 v55, v54, v55
	v_cvt_pk_bf16_f32 v54, v48, v49
	v_lshlrev_b64 v[48:49], 11, v[102:103]
	v_lshl_add_u64 v[48:49], v[76:77], 0, v[48:49]
	v_mov_b32_e32 v91, v1
	global_store_dwordx2 v[48:49], v[54:55], off
	v_lshl_add_u64 v[62:63], v[114:115], 0, v[90:91]
	global_load_dwordx4 v[54:57], v[72:73], off offset:1024
	s_nop 0
	global_load_dwordx4 v[62:65], v[62:63], off
	s_nop 0
	global_load_dwordx4 v[66:69], v[112:113], off offset:1024
	v_mov_b32_e32 v93, v1
	v_add_u32_e32 v88, s4, v88
	s_mov_b32 s4, 0x87ff
	s_waitcnt vmcnt(1)
	v_pk_add_f32 v[62:63], v[62:63], 1.0 op_sel_hi:[1,0]
	s_nop 0
	v_pk_mul_f32 v[54:55], v[54:55], v[62:63]
	v_pk_add_f32 v[62:63], v[64:65], 1.0 op_sel_hi:[1,0]
	s_waitcnt vmcnt(0)
	v_pk_fma_f32 v[14:15], v[14:15], v[54:55], v[66:67]
	v_pk_mul_f32 v[56:57], v[56:57], v[62:63]
	v_pk_fma_f32 v[16:17], v[16:17], v[56:57], v[68:69]
	v_cvt_pk_bf16_f32 v14, v14, v15
	v_cvt_pk_bf16_f32 v15, v16, v17
	global_store_dwordx2 v[34:35], v[14:15], off offset:512
	v_pk_mul_f32 v[14:15], v[26:27], v[104:105] op_sel_hi:[1,0]
	v_pk_mul_f32 v[16:17], v[28:29], v[104:105] op_sel_hi:[1,0]
	v_pk_fma_f32 v[14:15], v[14:15], v[54:55], v[66:67]
	v_pk_fma_f32 v[16:17], v[16:17], v[56:57], v[68:69]
	v_cvt_pk_bf16_f32 v14, v14, v15
	v_cvt_pk_bf16_f32 v15, v16, v17
	global_store_dwordx2 v[36:37], v[14:15], off offset:512
	v_pk_mul_f32 v[14:15], v[38:39], v[110:111] op_sel_hi:[1,0]
	v_pk_mul_f32 v[16:17], v[40:41], v[110:111] op_sel_hi:[1,0]
	v_pk_fma_f32 v[14:15], v[14:15], v[54:55], v[66:67]
	v_pk_fma_f32 v[16:17], v[16:17], v[56:57], v[68:69]
	v_cvt_pk_bf16_f32 v14, v14, v15
	v_cvt_pk_bf16_f32 v15, v16, v17
	global_store_dwordx2 v[46:47], v[14:15], off offset:512
	v_pk_mul_f32 v[14:15], v[58:59], v[108:109] op_sel_hi:[1,0]
	v_pk_mul_f32 v[16:17], v[60:61], v[108:109] op_sel_hi:[1,0]
	v_pk_fma_f32 v[14:15], v[14:15], v[54:55], v[66:67]
	v_pk_fma_f32 v[16:17], v[16:17], v[56:57], v[68:69]
	v_cvt_pk_bf16_f32 v14, v14, v15
	v_cvt_pk_bf16_f32 v15, v16, v17
	global_store_dwordx2 v[48:49], v[14:15], off offset:512
	v_lshl_add_u64 v[26:27], v[114:115], 0, v[92:93]
	global_load_dwordx4 v[14:17], v[72:73], off offset:2048
	s_nop 0
	global_load_dwordx4 v[26:29], v[26:27], off
	s_nop 0
	global_load_dwordx4 v[38:41], v[112:113], off offset:2048
	s_waitcnt vmcnt(1)
	v_pk_add_f32 v[26:27], v[26:27], 1.0 op_sel_hi:[1,0]
	s_nop 0
	v_pk_mul_f32 v[14:15], v[14:15], v[26:27]
	v_pk_add_f32 v[26:27], v[28:29], 1.0 op_sel_hi:[1,0]
	s_waitcnt vmcnt(0)
	v_pk_fma_f32 v[6:7], v[6:7], v[14:15], v[38:39]
	v_pk_mul_f32 v[16:17], v[16:17], v[26:27]
	v_pk_fma_f32 v[8:9], v[8:9], v[16:17], v[40:41]
	v_cvt_pk_bf16_f32 v6, v6, v7
	v_cvt_pk_bf16_f32 v7, v8, v9
	global_store_dwordx2 v[34:35], v[6:7], off offset:1024
	v_pk_mul_f32 v[6:7], v[18:19], v[104:105] op_sel_hi:[1,0]
	v_pk_mul_f32 v[8:9], v[20:21], v[104:105] op_sel_hi:[1,0]
	v_pk_fma_f32 v[6:7], v[6:7], v[14:15], v[38:39]
	v_pk_fma_f32 v[8:9], v[8:9], v[16:17], v[40:41]
	v_cvt_pk_bf16_f32 v6, v6, v7
	v_cvt_pk_bf16_f32 v7, v8, v9
	global_store_dwordx2 v[36:37], v[6:7], off offset:1024
	v_pk_mul_f32 v[6:7], v[30:31], v[110:111] op_sel_hi:[1,0]
	v_pk_mul_f32 v[8:9], v[32:33], v[110:111] op_sel_hi:[1,0]
	v_pk_fma_f32 v[6:7], v[6:7], v[14:15], v[38:39]
	v_pk_fma_f32 v[8:9], v[8:9], v[16:17], v[40:41]
	v_cvt_pk_bf16_f32 v6, v6, v7
	v_cvt_pk_bf16_f32 v7, v8, v9
	global_store_dwordx2 v[46:47], v[6:7], off offset:1024
	v_pk_mul_f32 v[6:7], v[50:51], v[108:109] op_sel_hi:[1,0]
	v_pk_mul_f32 v[8:9], v[52:53], v[108:109] op_sel_hi:[1,0]
	v_pk_fma_f32 v[6:7], v[6:7], v[14:15], v[38:39]
	v_pk_fma_f32 v[8:9], v[8:9], v[16:17], v[40:41]
	v_cvt_pk_bf16_f32 v6, v6, v7
	v_cvt_pk_bf16_f32 v7, v8, v9
	global_store_dwordx2 v[48:49], v[6:7], off offset:1024
	v_lshl_add_u64 v[14:15], v[114:115], 0, v[94:95]
	global_load_dwordx4 v[6:9], v[72:73], off offset:3072
	s_nop 0
	global_load_dwordx4 v[14:17], v[14:15], off
	s_nop 0
	global_load_dwordx4 v[18:21], v[112:113], off offset:3072
	s_waitcnt vmcnt(1)
	v_pk_add_f32 v[14:15], v[14:15], 1.0 op_sel_hi:[1,0]
	s_nop 0
	v_pk_mul_f32 v[6:7], v[6:7], v[14:15]
	v_pk_add_f32 v[14:15], v[16:17], 1.0 op_sel_hi:[1,0]
	s_waitcnt vmcnt(0)
	v_pk_fma_f32 v[2:3], v[2:3], v[6:7], v[18:19]
	v_pk_mul_f32 v[8:9], v[8:9], v[14:15]
	v_pk_fma_f32 v[4:5], v[4:5], v[8:9], v[20:21]
	v_cvt_pk_bf16_f32 v2, v2, v3
	v_cvt_pk_bf16_f32 v3, v4, v5
	global_store_dwordx2 v[34:35], v[2:3], off offset:1536
	v_pk_mul_f32 v[2:3], v[10:11], v[104:105] op_sel_hi:[1,0]
	v_pk_mul_f32 v[4:5], v[12:13], v[104:105] op_sel_hi:[1,0]
	v_pk_fma_f32 v[2:3], v[2:3], v[6:7], v[18:19]
	v_pk_fma_f32 v[4:5], v[4:5], v[8:9], v[20:21]
	v_cvt_pk_bf16_f32 v2, v2, v3
	v_cvt_pk_bf16_f32 v3, v4, v5
	global_store_dwordx2 v[36:37], v[2:3], off offset:1536
	v_pk_mul_f32 v[2:3], v[22:23], v[110:111] op_sel_hi:[1,0]
	v_pk_mul_f32 v[4:5], v[24:25], v[110:111] op_sel_hi:[1,0]
	v_pk_fma_f32 v[2:3], v[2:3], v[6:7], v[18:19]
	v_pk_fma_f32 v[4:5], v[4:5], v[8:9], v[20:21]
	v_cvt_pk_bf16_f32 v2, v2, v3
	v_cvt_pk_bf16_f32 v3, v4, v5
	global_store_dwordx2 v[46:47], v[2:3], off offset:1536
	v_pk_mul_f32 v[2:3], v[42:43], v[108:109] op_sel_hi:[1,0]
	v_pk_mul_f32 v[4:5], v[44:45], v[108:109] op_sel_hi:[1,0]
	v_pk_fma_f32 v[2:3], v[2:3], v[6:7], v[18:19]
	v_pk_fma_f32 v[4:5], v[4:5], v[8:9], v[20:21]
	v_cvt_pk_bf16_f32 v2, v2, v3
	v_add_u32_e32 v0, 0x8000, v88
	v_cmp_lt_i32_e32 vcc, s4, v0
	v_cvt_pk_bf16_f32 v3, v4, v5
	s_or_b64 s[38:39], vcc, s[38:39]
	global_store_dwordx2 v[48:49], v[2:3], off offset:1536
	s_andn2_b64 exec, exec, s[38:39]
	s_cbranch_execz .LBB0_1310
